# v_combo17 + non-temporal hint on p6a_prep's 32 streaming output stores
# speedup vs baseline: 1.0049x; 1.0049x over previous
.LBB0_552:
	s_bfe_u32 s50, s48, 0x30007
	s_lshl_b32 s51, s50, 7
	v_readlane_b32 s76, v247, 26
	v_or_b32_e32 v0, s51, v20
	v_readlane_b32 s82, v247, 32
	v_readlane_b32 s83, v247, 33
	v_lshlrev_b32_e32 v22, 2, v0
	s_mov_b64 s[54:55], s[82:83]
	v_lshl_add_u64 v[0:1], s[54:55], 0, v[22:23]
	s_ashr_i32 s42, s48, 10
	v_add_co_u32_e32 v0, vcc, 0x1000, v0
	s_and_b32 s49, s48, 0x7f
	s_nop 0
	v_addc_co_u32_e32 v1, vcc, 0, v1, vcc
	s_ashr_i32 s43, s42, 31
	global_load_dwordx2 v[0:1], v[0:1], off
	s_nop 0
	global_load_dwordx2 v[2:3], v22, s[82:83]
	s_lshl_b64 s[44:45], s[42:43], 23
	v_lshl_add_u32 v22, s49, 16, v94
	v_lshl_add_u64 v[4:5], s[44:45], 0, v[22:23]
	v_or_b32_e32 v4, s51, v4
	v_or_b32_e32 v4, v4, v20
	v_lshlrev_b64 v[26:27], 1, v[4:5]
	v_lshl_add_u64 v[34:35], s[34:35], 0, v[26:27]
	v_add_co_u32_e32 v4, vcc, s33, v34
	v_lshl_add_u64 v[32:33], s[36:37], 0, v[26:27]
	s_nop 0
	v_addc_co_u32_e32 v5, vcc, 0, v35, vcc
	v_add_co_u32_e32 v6, vcc, s33, v32
	v_lshl_add_u64 v[30:31], s[38:39], 0, v[26:27]
	s_nop 0
	v_addc_co_u32_e32 v7, vcc, 0, v33, vcc
	global_load_dword v16, v[32:33], off
	global_load_dword v46, v[30:31], off offset:2048
	global_load_dword v99, v[4:5], off offset:2048
	global_load_dword v17, v[6:7], off offset:2048
	global_load_dword v18, v[32:33], off offset:2048
	v_add_co_u32_e32 v4, vcc, s46, v32
	v_readlane_b32 s77, v247, 27
	s_nop 0
	v_addc_co_u32_e32 v5, vcc, 0, v33, vcc
	v_add_co_u32_e32 v6, vcc, s46, v34
	global_load_dword v19, v[4:5], off offset:-4096
	global_load_dword v28, v[4:5], off
	v_addc_co_u32_e32 v7, vcc, 0, v35, vcc
	v_add_co_u32_e32 v8, vcc, s33, v30
	v_readlane_b32 s78, v247, 28
	s_nop 0
	v_addc_co_u32_e32 v9, vcc, 0, v31, vcc
	v_add_co_u32_e32 v10, vcc, s46, v30
	v_readlane_b32 s79, v247, 29
	s_nop 0
	v_addc_co_u32_e32 v11, vcc, 0, v31, vcc
	global_load_dword v47, v[10:11], off
	global_load_dword v52, v[10:11], off offset:2048
	global_load_dword v29, v[4:5], off offset:2048
	v_add_co_u32_e32 v4, vcc, s47, v34
	v_readlane_b32 s80, v247, 30
	s_nop 0
	v_addc_co_u32_e32 v5, vcc, 0, v35, vcc
	v_add_co_u32_e32 v12, vcc, s47, v32
	v_readlane_b32 s81, v247, 31
	s_nop 0
	v_addc_co_u32_e32 v13, vcc, 0, v33, vcc
	global_load_dword v36, v[12:13], off
	v_add_co_u32_e32 v14, vcc, s47, v30
	v_readlane_b32 s84, v247, 34
	s_nop 0
	v_addc_co_u32_e32 v15, vcc, 0, v31, vcc
	global_load_dword v53, v[30:31], off
	global_load_dword v112, v[34:35], off
	global_load_dword v113, v[34:35], off offset:2048
	global_load_dword v37, v[14:15], off offset:2048
	global_load_dword v38, v[12:13], off offset:2048
	global_load_dword v54, v[10:11], off offset:-4096
	global_load_dword v100, v[6:7], off
	global_load_dword v98, v[6:7], off offset:2048
	global_load_dword v55, v[14:15], off
	global_load_dword v101, v[6:7], off offset:-4096
	global_load_dword v60, v[8:9], off offset:2048
	global_load_dword v97, v[4:5], off
	global_load_dword v22, v[4:5], off offset:2048
	v_readlane_b32 s85, v247, 35
	v_readlane_b32 s86, v247, 36
	v_readlane_b32 s87, v247, 37
	v_readlane_b32 s88, v247, 38
	v_readlane_b32 s89, v247, 39
	v_readlane_b32 s90, v247, 40
	v_readlane_b32 s91, v247, 41
	s_waitcnt vmcnt(24)
	v_sub_f32_e32 v0, v0, v2
	v_sub_f32_e32 v1, v1, v3
	v_mul_f32_e32 v0, 0x3fb8aa3b, v0
	v_mul_f32_e32 v1, 0x3fb8aa3b, v1
	v_exp_f32_e32 v0, v0
	v_exp_f32_e32 v1, v1
	s_waitcnt vmcnt(23)
	v_lshlrev_b32_e32 v2, 16, v16
	v_pk_add_f32 v[0:1], v[0:1], 1.0 op_sel_hi:[1,0]
	s_waitcnt vmcnt(19)
	v_lshlrev_b32_e32 v4, 16, v18
	v_and_b32_e32 v5, 0xffff0000, v18
	v_div_scale_f32 v18, s[44:45], v1, v1, 1.0
	v_and_b32_e32 v3, 0xffff0000, v16
	v_mul_f32_e32 v2, 0xbfb8aa3b, v2
	v_mul_f32_e32 v3, 0xbfb8aa3b, v3
	s_waitcnt vmcnt(18)
	v_lshlrev_b32_e32 v6, 16, v19
	v_and_b32_e32 v7, 0xffff0000, v19
	v_rcp_f32_e32 v19, v18
	s_waitcnt vmcnt(17)
	v_lshlrev_b32_e32 v10, 16, v28
	v_and_b32_e32 v11, 0xffff0000, v28
	v_mul_f32_e32 v4, 0xbfb8aa3b, v4
	v_fma_f32 v28, -v18, v19, 1.0
	v_fmac_f32_e32 v19, v28, v19
	v_div_scale_f32 v28, vcc, 1.0, v1, 1.0
	v_mul_f32_e32 v5, 0xbfb8aa3b, v5
	v_exp_f32_e32 v2, v2
	v_exp_f32_e32 v3, v3
	v_exp_f32_e32 v4, v4
	s_waitcnt vmcnt(14)
	v_lshlrev_b32_e32 v12, 16, v29
	v_and_b32_e32 v13, 0xffff0000, v29
	v_mul_f32_e32 v29, v28, v19
	v_exp_f32_e32 v5, v5
	v_mul_f32_e32 v6, 0xbfb8aa3b, v6
	v_mul_f32_e32 v7, 0xbfb8aa3b, v7
	v_lshlrev_b32_e32 v8, 16, v17
	v_and_b32_e32 v9, 0xffff0000, v17
	v_exp_f32_e32 v6, v6
	v_exp_f32_e32 v7, v7
	v_mul_f32_e32 v8, 0xbfb8aa3b, v8
	s_waitcnt vmcnt(13)
	v_lshlrev_b32_e32 v14, 16, v36
	v_and_b32_e32 v15, 0xffff0000, v36
	v_fma_f32 v36, -v18, v29, v28
	v_fmac_f32_e32 v29, v36, v19
	v_fma_f32 v18, -v18, v29, v28
	v_div_scale_f32 v28, s[44:45], v0, v0, 1.0
	v_rcp_f32_e32 v36, v28
	v_div_fmas_f32 v18, v18, v19, v29
	v_div_fixup_f32 v1, v18, v1, 1.0
	v_mul_f32_e32 v9, 0xbfb8aa3b, v9
	v_fma_f32 v18, -v28, v36, 1.0
	v_fmac_f32_e32 v36, v18, v36
	v_div_scale_f32 v18, vcc, 1.0, v0, 1.0
	v_exp_f32_e32 v8, v8
	v_exp_f32_e32 v9, v9
	v_mul_f32_e32 v10, 0xbfb8aa3b, v10
	v_mul_f32_e32 v11, 0xbfb8aa3b, v11
	v_mul_f32_e32 v19, v18, v36
	v_exp_f32_e32 v10, v10
	v_exp_f32_e32 v11, v11
	v_mul_f32_e32 v12, 0xbfb8aa3b, v12
	v_mul_f32_e32 v13, 0xbfb8aa3b, v13
	v_fma_f32 v29, -v28, v19, v18
	v_add_f32_e32 v2, 1.0, v2
	v_add_f32_e32 v3, 1.0, v3
	v_add_f32_e32 v4, 1.0, v4
	v_add_f32_e32 v5, 1.0, v5
	v_exp_f32_e32 v12, v12
	v_exp_f32_e32 v13, v13
	v_mul_f32_e32 v14, 0xbfb8aa3b, v14
	v_mul_f32_e32 v15, 0xbfb8aa3b, v15
	s_waitcnt vmcnt(8)
	v_lshlrev_b32_e32 v16, 16, v38
	v_and_b32_e32 v17, 0xffff0000, v38
	v_fmac_f32_e32 v19, v29, v36
	v_rcp_f32_e32 v2, v2
	v_rcp_f32_e32 v3, v3
	v_rcp_f32_e32 v4, v4
	v_rcp_f32_e32 v5, v5
	v_add_f32_e32 v6, 1.0, v6
	v_add_f32_e32 v7, 1.0, v7
	v_exp_f32_e32 v14, v14
	v_exp_f32_e32 v15, v15
	v_mul_f32_e32 v16, 0xbfb8aa3b, v16
	v_mul_f32_e32 v17, 0xbfb8aa3b, v17
	v_fma_f32 v18, -v28, v19, v18
	v_rcp_f32_e32 v6, v6
	v_rcp_f32_e32 v7, v7
	v_add_f32_e32 v8, 1.0, v8
	v_add_f32_e32 v9, 1.0, v9
	v_exp_f32_e32 v16, v16
	v_exp_f32_e32 v17, v17
	v_div_fmas_f32 v18, v18, v36, v19
	v_rcp_f32_e32 v8, v8
	v_rcp_f32_e32 v9, v9
	v_add_f32_e32 v10, 1.0, v10
	v_add_f32_e32 v11, 1.0, v11
	v_div_fixup_f32 v0, v18, v0, 1.0
	v_rcp_f32_e32 v10, v10
	v_rcp_f32_e32 v11, v11
	v_add_f32_e32 v12, 1.0, v12
	v_add_f32_e32 v13, 1.0, v13
	v_pk_add_f32 v[18:19], v[0:1], 1.0 op_sel_hi:[1,0] neg_lo:[1,0] neg_hi:[1,0]
	v_rcp_f32_e32 v12, v12
	v_rcp_f32_e32 v13, v13
	v_add_f32_e32 v14, 1.0, v14
	v_add_f32_e32 v15, 1.0, v15
	v_pk_fma_f32 v[86:87], v[18:19], v[2:3], v[0:1]
	v_pk_fma_f32 v[78:79], v[18:19], v[4:5], v[0:1]
	v_lshlrev_b32_e32 v2, 16, v37
	v_and_b32_e32 v3, 0xffff0000, v37
	s_waitcnt vmcnt(4)
	v_lshlrev_b32_e32 v4, 16, v55
	v_and_b32_e32 v5, 0xffff0000, v55
	v_rcp_f32_e32 v14, v14
	v_rcp_f32_e32 v15, v15
	v_add_f32_e32 v16, 1.0, v16
	v_add_f32_e32 v17, 1.0, v17
	v_pk_fma_f32 v[64:65], v[18:19], v[6:7], v[0:1]
	v_mul_f32_e32 v2, 0xbfb8aa3b, v2
	v_mul_f32_e32 v3, 0xbfb8aa3b, v3
	v_mul_f32_e32 v4, 0xbfb8aa3b, v4
	v_mul_f32_e32 v5, 0xbfb8aa3b, v5
	v_lshlrev_b32_e32 v6, 16, v52
	v_and_b32_e32 v7, 0xffff0000, v52
	v_rcp_f32_e32 v16, v16
	v_rcp_f32_e32 v17, v17
	v_pk_fma_f32 v[56:57], v[18:19], v[8:9], v[0:1]
	v_exp_f32_e32 v2, v2
	v_exp_f32_e32 v3, v3
	v_exp_f32_e32 v4, v4
	v_exp_f32_e32 v5, v5
	v_mul_f32_e32 v6, 0xbfb8aa3b, v6
	v_mul_f32_e32 v7, 0xbfb8aa3b, v7
	v_lshlrev_b32_e32 v8, 16, v47
	v_and_b32_e32 v9, 0xffff0000, v47
	v_pk_fma_f32 v[48:49], v[18:19], v[10:11], v[0:1]
	v_exp_f32_e32 v6, v6
	v_exp_f32_e32 v7, v7
	v_mul_f32_e32 v8, 0xbfb8aa3b, v8
	v_mul_f32_e32 v9, 0xbfb8aa3b, v9
	s_waitcnt vmcnt(2)
	v_lshlrev_b32_e32 v10, 16, v60
	v_and_b32_e32 v11, 0xffff0000, v60
	v_pk_fma_f32 v[42:43], v[18:19], v[12:13], v[0:1]
	v_exp_f32_e32 v8, v8
	v_exp_f32_e32 v9, v9
	v_mul_f32_e32 v10, 0xbfb8aa3b, v10
	v_mul_f32_e32 v11, 0xbfb8aa3b, v11
	v_lshlrev_b32_e32 v12, 16, v54
	v_and_b32_e32 v13, 0xffff0000, v54
	v_pk_fma_f32 v[38:39], v[18:19], v[14:15], v[0:1]
	v_exp_f32_e32 v10, v10
	v_exp_f32_e32 v11, v11
	v_mul_f32_e32 v12, 0xbfb8aa3b, v12
	v_mul_f32_e32 v13, 0xbfb8aa3b, v13
	v_lshlrev_b32_e32 v14, 16, v46
	v_and_b32_e32 v15, 0xffff0000, v46
	v_pk_fma_f32 v[28:29], v[18:19], v[16:17], v[0:1]
	v_add_f32_e32 v2, 1.0, v2
	v_add_f32_e32 v3, 1.0, v3
	v_add_f32_e32 v4, 1.0, v4
	v_add_f32_e32 v5, 1.0, v5
	v_exp_f32_e32 v12, v12
	v_exp_f32_e32 v13, v13
	v_mul_f32_e32 v14, 0xbfb8aa3b, v14
	v_mul_f32_e32 v15, 0xbfb8aa3b, v15
	v_lshlrev_b32_e32 v16, 16, v53
	v_and_b32_e32 v17, 0xffff0000, v53
	v_rcp_f32_e32 v2, v2
	v_rcp_f32_e32 v3, v3
	v_rcp_f32_e32 v4, v4
	v_rcp_f32_e32 v5, v5
	v_add_f32_e32 v6, 1.0, v6
	v_add_f32_e32 v7, 1.0, v7
	v_exp_f32_e32 v14, v14
	v_exp_f32_e32 v15, v15
	v_mul_f32_e32 v16, 0xbfb8aa3b, v16
	v_mul_f32_e32 v17, 0xbfb8aa3b, v17
	v_rcp_f32_e32 v6, v6
	v_rcp_f32_e32 v7, v7
	v_add_f32_e32 v8, 1.0, v8
	v_add_f32_e32 v9, 1.0, v9
	v_exp_f32_e32 v16, v16
	v_exp_f32_e32 v17, v17
	v_rcp_f32_e32 v8, v8
	v_rcp_f32_e32 v9, v9
	v_add_f32_e32 v10, 1.0, v10
	v_add_f32_e32 v11, 1.0, v11
	v_rcp_f32_e32 v10, v10
	v_rcp_f32_e32 v11, v11
	v_add_f32_e32 v12, 1.0, v12
	v_add_f32_e32 v13, 1.0, v13
	v_rcp_f32_e32 v12, v12
	v_rcp_f32_e32 v13, v13
	v_add_f32_e32 v14, 1.0, v14
	v_add_f32_e32 v15, 1.0, v15
	v_pk_fma_f32 v[46:47], v[18:19], v[2:3], v[0:1]
	v_pk_fma_f32 v[54:55], v[18:19], v[4:5], v[0:1]
	v_pk_mul_f32 v[82:83], v[86:87], v[78:79]
	v_rcp_f32_e32 v14, v14
	v_rcp_f32_e32 v15, v15
	v_add_f32_e32 v16, 1.0, v16
	v_add_f32_e32 v17, 1.0, v17
	v_pk_mul_f32 v[60:61], v[54:55], v[46:47]
	v_pk_fma_f32 v[62:63], v[18:19], v[6:7], v[0:1]
	v_pk_mul_f32 v[72:73], v[82:83], v[64:65]
	v_rcp_f32_e32 v16, v16
	v_rcp_f32_e32 v17, v17
	v_pk_mul_f32 v[76:77], v[62:63], v[60:61]
	v_pk_fma_f32 v[80:81], v[18:19], v[8:9], v[0:1]
	v_pk_mul_f32 v[58:59], v[72:73], v[56:57]
	v_pk_mul_f32 v[84:85], v[80:81], v[76:77]
	v_pk_fma_f32 v[88:89], v[18:19], v[10:11], v[0:1]
	v_pk_mul_f32 v[50:51], v[58:59], v[48:49]
	v_pk_mul_f32 v[90:91], v[88:89], v[84:85]
	v_pk_fma_f32 v[92:93], v[18:19], v[12:13], v[0:1]
	v_pk_mul_f32 v[44:45], v[50:51], v[42:43]
	v_pk_mul_f32 v[102:103], v[92:93], v[90:91]
	v_pk_fma_f32 v[104:105], v[18:19], v[14:15], v[0:1]
	v_pk_mul_f32 v[40:41], v[44:45], v[38:39]
	v_pk_mul_f32 v[106:107], v[104:105], v[102:103]
	v_pk_fma_f32 v[108:109], v[18:19], v[16:17], v[0:1]
	v_pk_mul_f32 v[36:37], v[40:41], v[28:29]
	v_pk_mul_f32 v[110:111], v[108:109], v[106:107]
	ds_write2st64_b64 v95, v[36:37], v[110:111] offset1:8
	s_waitcnt lgkmcnt(0)
	s_barrier
	ds_read2st64_b64 v[8:11], v21 offset1:1
	ds_read2st64_b64 v[12:15], v21 offset0:2 offset1:3
	ds_read2st64_b64 v[0:3], v21 offset0:9 offset1:10
	v_lshlrev_b32_e32 v118, 16, v112
	v_and_b32_e32 v112, 0xffff0000, v112
	s_waitcnt lgkmcnt(2)
	v_cndmask_b32_e64 v4, v9, 1.0, s[0:1]
	v_cndmask_b32_e64 v5, v8, 1.0, s[0:1]
	v_mul_f32_e32 v6, v5, v10
	v_mul_f32_e32 v7, v4, v11
	v_cndmask_b32_e64 v16, v4, v7, s[2:3]
	v_cndmask_b32_e64 v17, v5, v6, s[2:3]
	s_waitcnt lgkmcnt(1)
	v_mul_f32_e32 v52, v17, v12
	v_mul_f32_e32 v53, v16, v13
	v_cndmask_b32_e64 v16, v16, v53, s[4:5]
	v_cndmask_b32_e64 v17, v17, v52, s[4:5]
	v_pk_mul_f32 v[8:9], v[8:9], v[10:11]
	ds_read2st64_b64 v[4:7], v21 offset0:11 offset1:12
	v_mul_f32_e32 v52, v17, v14
	v_mul_f32_e32 v53, v16, v15
	v_pk_mul_f32 v[8:9], v[8:9], v[12:13]
	v_cndmask_b32_e64 v16, v16, v53, s[8:9]
	v_cndmask_b32_e64 v17, v17, v52, s[8:9]
	v_pk_mul_f32 v[52:53], v[8:9], v[14:15]
	ds_read2st64_b64 v[8:11], v21 offset0:4 offset1:5
	s_waitcnt lgkmcnt(2)
	v_cndmask_b32_e64 v18, 1.0, v1, s[0:1]
	v_cndmask_b32_e64 v19, 1.0, v0, s[0:1]
	v_mul_f32_e32 v19, v19, v2
	v_mul_f32_e32 v18, v18, v3
	v_cndmask_b32_e64 v18, 1.0, v18, s[6:7]
	v_cndmask_b32_e64 v19, 1.0, v19, s[6:7]
	s_waitcnt lgkmcnt(1)
	v_mul_f32_e32 v12, v19, v4
	v_mul_f32_e32 v13, v18, v5
	v_cndmask_b32_e64 v18, 1.0, v13, s[10:11]
	v_cndmask_b32_e64 v19, 1.0, v12, s[10:11]
	ds_read2st64_b64 v[12:15], v21 offset0:6 offset1:7
	s_waitcnt lgkmcnt(1)
	v_mul_f32_e32 v66, v17, v8
	v_mul_f32_e32 v67, v16, v9
	v_cndmask_b32_e64 v67, v16, v67, s[12:13]
	v_cndmask_b32_e64 v66, v17, v66, s[12:13]
	v_mul_f32_e32 v16, v19, v6
	v_mul_f32_e32 v17, v18, v7
	v_cndmask_b32_e64 v68, 1.0, v17, s[14:15]
	v_cndmask_b32_e64 v69, 1.0, v16, s[14:15]
	ds_read2st64_b64 v[16:19], v21 offset0:13 offset1:14
	v_mul_f32_e32 v70, v66, v10
	v_mul_f32_e32 v71, v67, v11
	v_cndmask_b32_e64 v67, v67, v71, s[16:17]
	v_cndmask_b32_e64 v66, v66, v70, s[16:17]
	ds_read_b64 v[70:71], v21 offset:7680
	s_waitcnt lgkmcnt(1)
	v_mul_f32_e32 v69, v69, v16
	v_mul_f32_e32 v68, v68, v17
	v_cndmask_b32_e64 v68, 1.0, v68, s[18:19]
	v_cndmask_b32_e64 v69, 1.0, v69, s[18:19]
	v_mul_f32_e32 v74, v66, v12
	v_mul_f32_e32 v75, v67, v13
	v_cndmask_b32_e64 v67, v67, v75, s[20:21]
	v_cndmask_b32_e64 v66, v66, v74, s[20:21]
	v_mul_f32_e32 v69, v69, v18
	v_mul_f32_e32 v68, v68, v19
	v_cndmask_b32_e64 v68, 1.0, v68, s[22:23]
	v_cndmask_b32_e64 v69, 1.0, v69, s[22:23]
	v_mul_f32_e32 v74, v66, v14
	v_mul_f32_e32 v75, v67, v15
	v_cndmask_b32_e64 v114, v67, v75, s[24:25]
	v_cndmask_b32_e64 v115, v66, v74, s[24:25]
	s_waitcnt lgkmcnt(0)
	v_mul_f32_e32 v66, v69, v70
	v_mul_f32_e32 v67, v68, v71
	v_cndmask_b32_e64 v116, 1.0, v67, s[26:27]
	v_cndmask_b32_e64 v117, 1.0, v66, s[26:27]
	v_pk_mul_f32 v[66:67], v[6:7], v[16:17]
	v_rcp_f32_e32 v74, v52
	v_pk_mul_f32 v[66:67], v[66:67], v[18:19]
	v_rcp_f32_e32 v75, v53
	v_pk_mul_f32 v[68:69], v[66:67], v[70:71]
	v_mul_f32_e32 v115, v74, v115
	v_rcp_f32_e32 v66, v68
	v_rcp_f32_e32 v67, v69
	v_mul_f32_e32 v114, v75, v114
	v_mul_f32_e32 v119, v86, v115
	v_mul_f32_e32 v117, v66, v117
	v_mul_f32_e32 v116, v67, v116
	v_mul_f32_e32 v120, v87, v114
	v_mul_f32_e32 v121, v110, v117
	v_mul_f32_e32 v122, v111, v116
	v_rcp_f32_e32 v110, v119
	v_rcp_f32_e32 v111, v120
	v_mul_f32_e32 v123, v119, v118
	v_mul_f32_e32 v124, v120, v112
	v_cvt_pk_bf16_f32 v119, v123, v124
	global_store_dword v[34:35], v119, off nt
	v_pk_add_f32 v[34:35], v[86:87], 1.0 op_sel_hi:[1,0] neg_lo:[1,0] neg_hi:[1,0]
	v_and_b32_e32 v87, 0xffff0000, v113
	v_pk_mul_f32 v[34:35], v[34:35], v[110:111]
	v_pk_add_f32 v[28:29], v[28:29], 1.0 op_sel_hi:[1,0] neg_lo:[1,0] neg_hi:[1,0]
	v_cvt_pk_bf16_f32 v34, v34, v35
	global_store_dword v[32:33], v34, off nt
	v_mul_f32_e32 v32, v121, v118
	v_mul_f32_e32 v33, v122, v112
	v_cvt_pk_bf16_f32 v86, v32, v33
	v_rcp_f32_e32 v32, v121
	v_rcp_f32_e32 v33, v122
	v_lshl_add_u64 v[34:35], s[40:41], 0, v[26:27]
	global_store_dword v[34:35], v86, off nt
	v_pk_add_f32 v[34:35], v[108:109], 1.0 op_sel_hi:[1,0] neg_lo:[1,0] neg_hi:[1,0]
	v_lshlrev_b32_e32 v86, 16, v113
	v_pk_mul_f32 v[32:33], v[34:35], v[32:33]
	s_nop 0
	v_cvt_pk_bf16_f32 v32, v32, v33
	global_store_dword v[30:31], v32, off nt
	v_mul_f32_e32 v32, v82, v115
	v_mul_f32_e32 v33, v83, v114
	v_mul_f32_e32 v30, v32, v86
	v_mul_f32_e32 v31, v33, v87
	v_rcp_f32_e32 v32, v32
	v_rcp_f32_e32 v33, v33
	v_mul_f32_e32 v82, v106, v117
	v_cvt_pk_bf16_f32 v106, v30, v31
	v_or_b32_e32 v30, 0x800, v26
	v_mov_b32_e32 v31, v27
	v_lshl_add_u64 v[34:35], s[34:35], 0, v[30:31]
	global_store_dword v[34:35], v106, off nt
	v_pk_add_f32 v[34:35], v[78:79], 1.0 op_sel_hi:[1,0] neg_lo:[1,0] neg_hi:[1,0]
	v_mul_f32_e32 v83, v107, v116
	v_pk_mul_f32 v[32:33], v[34:35], v[32:33]
	v_and_b32_e32 v79, 0xffff0000, v101
	v_cvt_pk_bf16_f32 v34, v32, v33
	v_lshl_add_u64 v[32:33], s[36:37], 0, v[30:31]
	global_store_dword v[32:33], v34, off nt
	v_mul_f32_e32 v32, v82, v86
	v_mul_f32_e32 v33, v83, v87
	v_cvt_pk_bf16_f32 v78, v32, v33
	v_rcp_f32_e32 v32, v82
	v_rcp_f32_e32 v33, v83
	v_lshl_add_u64 v[34:35], s[40:41], 0, v[30:31]
	global_store_dword v[34:35], v78, off nt
	v_pk_add_f32 v[34:35], v[104:105], 1.0 op_sel_hi:[1,0] neg_lo:[1,0] neg_hi:[1,0]
	v_lshl_add_u64 v[30:31], s[38:39], 0, v[30:31]
	v_pk_mul_f32 v[32:33], v[34:35], v[32:33]
	v_lshlrev_b32_e32 v78, 16, v101
	v_cvt_pk_bf16_f32 v32, v32, v33
	global_store_dword v[30:31], v32, off nt
	v_mul_f32_e32 v32, v72, v115
	v_mul_f32_e32 v33, v73, v114
	v_mul_f32_e32 v30, v32, v78
	v_mul_f32_e32 v31, v33, v79
	v_rcp_f32_e32 v32, v32
	v_rcp_f32_e32 v33, v33
	v_cvt_pk_bf16_f32 v82, v30, v31
	v_or_b32_e32 v30, 0x1000, v26
	v_mov_b32_e32 v31, v27
	v_lshl_add_u64 v[34:35], s[34:35], 0, v[30:31]
	global_store_dword v[34:35], v82, off nt
	v_pk_add_f32 v[34:35], v[64:65], 1.0 op_sel_hi:[1,0] neg_lo:[1,0] neg_hi:[1,0]
	v_mul_f32_e32 v72, v102, v117
	v_pk_mul_f32 v[32:33], v[34:35], v[32:33]
	v_mul_f32_e32 v73, v103, v116
	v_cvt_pk_bf16_f32 v34, v32, v33
	v_lshl_add_u64 v[32:33], s[36:37], 0, v[30:31]
	global_store_dword v[32:33], v34, off nt
	v_mul_f32_e32 v32, v72, v78
	v_mul_f32_e32 v33, v73, v79
	v_cvt_pk_bf16_f32 v64, v32, v33
	v_rcp_f32_e32 v32, v72
	v_rcp_f32_e32 v33, v73
	v_lshl_add_u64 v[34:35], s[40:41], 0, v[30:31]
	global_store_dword v[34:35], v64, off nt
	v_pk_add_f32 v[34:35], v[92:93], 1.0 op_sel_hi:[1,0] neg_lo:[1,0] neg_hi:[1,0]
	v_lshl_add_u64 v[30:31], s[38:39], 0, v[30:31]
	v_pk_mul_f32 v[32:33], v[34:35], v[32:33]
	v_lshlrev_b32_e32 v64, 16, v99
	v_cvt_pk_bf16_f32 v32, v32, v33
	global_store_dword v[30:31], v32, off nt
	v_and_b32_e32 v65, 0xffff0000, v99
	v_mul_f32_e32 v32, v58, v115
	v_mul_f32_e32 v33, v59, v114
	v_mul_f32_e32 v30, v32, v64
	v_mul_f32_e32 v31, v33, v65
	v_rcp_f32_e32 v32, v32
	v_rcp_f32_e32 v33, v33
	v_cvt_pk_bf16_f32 v72, v30, v31
	v_or_b32_e32 v30, 0x1800, v26
	v_mov_b32_e32 v31, v27
	v_lshl_add_u64 v[34:35], s[34:35], 0, v[30:31]
	global_store_dword v[34:35], v72, off nt
	v_pk_add_f32 v[34:35], v[56:57], 1.0 op_sel_hi:[1,0] neg_lo:[1,0] neg_hi:[1,0]
	v_mul_f32_e32 v58, v90, v117
	v_pk_mul_f32 v[32:33], v[34:35], v[32:33]
	v_mul_f32_e32 v59, v91, v116
	v_cvt_pk_bf16_f32 v34, v32, v33
	v_lshl_add_u64 v[32:33], s[36:37], 0, v[30:31]
	global_store_dword v[32:33], v34, off nt
	v_mul_f32_e32 v32, v58, v64
	v_mul_f32_e32 v33, v59, v65
	v_cvt_pk_bf16_f32 v56, v32, v33
	v_rcp_f32_e32 v32, v58
	v_rcp_f32_e32 v33, v59
	v_lshl_add_u64 v[34:35], s[40:41], 0, v[30:31]
	global_store_dword v[34:35], v56, off nt
	v_pk_add_f32 v[34:35], v[88:89], 1.0 op_sel_hi:[1,0] neg_lo:[1,0] neg_hi:[1,0]
	v_lshl_add_u64 v[30:31], s[38:39], 0, v[30:31]
	v_pk_mul_f32 v[32:33], v[34:35], v[32:33]
	v_lshlrev_b32_e32 v56, 16, v100
	v_cvt_pk_bf16_f32 v32, v32, v33
	global_store_dword v[30:31], v32, off nt
	v_and_b32_e32 v57, 0xffff0000, v100
	v_mul_f32_e32 v32, v50, v115
	v_mul_f32_e32 v33, v51, v114
	v_mul_f32_e32 v30, v32, v56
	v_mul_f32_e32 v31, v33, v57
	v_rcp_f32_e32 v32, v32
	v_rcp_f32_e32 v33, v33
	v_cvt_pk_bf16_f32 v58, v30, v31
	v_or_b32_e32 v30, 0x2000, v26
	v_mov_b32_e32 v31, v27
	v_lshl_add_u64 v[34:35], s[34:35], 0, v[30:31]
	global_store_dword v[34:35], v58, off nt
	v_pk_add_f32 v[34:35], v[48:49], 1.0 op_sel_hi:[1,0] neg_lo:[1,0] neg_hi:[1,0]
	v_mul_f32_e32 v50, v84, v117
	v_pk_mul_f32 v[32:33], v[34:35], v[32:33]
	v_mul_f32_e32 v51, v85, v116
	v_cvt_pk_bf16_f32 v34, v32, v33
	v_lshl_add_u64 v[32:33], s[36:37], 0, v[30:31]
	global_store_dword v[32:33], v34, off nt
	v_mul_f32_e32 v32, v50, v56
	v_mul_f32_e32 v33, v51, v57
	v_cvt_pk_bf16_f32 v48, v32, v33
	v_rcp_f32_e32 v32, v50
	v_rcp_f32_e32 v33, v51
	v_lshl_add_u64 v[34:35], s[40:41], 0, v[30:31]
	global_store_dword v[34:35], v48, off nt
	v_pk_add_f32 v[34:35], v[80:81], 1.0 op_sel_hi:[1,0] neg_lo:[1,0] neg_hi:[1,0]
	v_lshl_add_u64 v[30:31], s[38:39], 0, v[30:31]
	v_pk_mul_f32 v[32:33], v[34:35], v[32:33]
	v_lshlrev_b32_e32 v48, 16, v98
	v_cvt_pk_bf16_f32 v32, v32, v33
	global_store_dword v[30:31], v32, off nt
	v_and_b32_e32 v49, 0xffff0000, v98
	v_mul_f32_e32 v32, v44, v115
	v_mul_f32_e32 v33, v45, v114
	v_mul_f32_e32 v30, v32, v48
	v_mul_f32_e32 v31, v33, v49
	v_rcp_f32_e32 v32, v32
	v_rcp_f32_e32 v33, v33
	v_cvt_pk_bf16_f32 v50, v30, v31
	v_or_b32_e32 v30, 0x2800, v26
	v_mov_b32_e32 v31, v27
	v_lshl_add_u64 v[34:35], s[34:35], 0, v[30:31]
	global_store_dword v[34:35], v50, off nt
	v_pk_add_f32 v[34:35], v[42:43], 1.0 op_sel_hi:[1,0] neg_lo:[1,0] neg_hi:[1,0]
	v_mul_f32_e32 v44, v76, v117
	v_pk_mul_f32 v[32:33], v[34:35], v[32:33]
	v_mul_f32_e32 v45, v77, v116
	v_cvt_pk_bf16_f32 v34, v32, v33
	v_lshl_add_u64 v[32:33], s[36:37], 0, v[30:31]
	global_store_dword v[32:33], v34, off nt
	v_mul_f32_e32 v32, v44, v48
	v_mul_f32_e32 v33, v45, v49
	v_cvt_pk_bf16_f32 v42, v32, v33
	v_rcp_f32_e32 v32, v44
	v_rcp_f32_e32 v33, v45
	v_lshl_add_u64 v[34:35], s[40:41], 0, v[30:31]
	global_store_dword v[34:35], v42, off nt
	v_pk_add_f32 v[34:35], v[62:63], 1.0 op_sel_hi:[1,0] neg_lo:[1,0] neg_hi:[1,0]
	v_lshl_add_u64 v[30:31], s[38:39], 0, v[30:31]
	v_pk_mul_f32 v[32:33], v[34:35], v[32:33]
	s_waitcnt vmcnt(24)
	v_lshlrev_b32_e32 v42, 16, v97
	v_cvt_pk_bf16_f32 v32, v32, v33
	global_store_dword v[30:31], v32, off nt
	v_and_b32_e32 v43, 0xffff0000, v97
	v_mul_f32_e32 v32, v40, v115
	v_mul_f32_e32 v33, v41, v114
	v_mul_f32_e32 v30, v32, v42
	v_mul_f32_e32 v31, v33, v43
	v_rcp_f32_e32 v32, v32
	v_rcp_f32_e32 v33, v33
	v_cvt_pk_bf16_f32 v44, v30, v31
	v_or_b32_e32 v30, 0x3000, v26
	v_mov_b32_e32 v31, v27
	v_lshl_add_u64 v[34:35], s[34:35], 0, v[30:31]
	global_store_dword v[34:35], v44, off nt
	v_pk_add_f32 v[34:35], v[38:39], 1.0 op_sel_hi:[1,0] neg_lo:[1,0] neg_hi:[1,0]
	v_mul_f32_e32 v40, v60, v117
	v_pk_mul_f32 v[32:33], v[34:35], v[32:33]
	v_mul_f32_e32 v41, v61, v116
	v_cvt_pk_bf16_f32 v34, v32, v33
	v_lshl_add_u64 v[32:33], s[36:37], 0, v[30:31]
	global_store_dword v[32:33], v34, off nt
	v_mul_f32_e32 v32, v40, v42
	v_mul_f32_e32 v33, v41, v43
	v_cvt_pk_bf16_f32 v38, v32, v33
	v_rcp_f32_e32 v32, v40
	v_rcp_f32_e32 v33, v41
	v_lshl_add_u64 v[34:35], s[40:41], 0, v[30:31]
	global_store_dword v[34:35], v38, off nt
	v_pk_add_f32 v[34:35], v[54:55], 1.0 op_sel_hi:[1,0] neg_lo:[1,0] neg_hi:[1,0]
	v_lshl_add_u64 v[30:31], s[38:39], 0, v[30:31]
	v_pk_mul_f32 v[32:33], v[34:35], v[32:33]
	s_waitcnt vmcnt(27)
	v_lshlrev_b32_e32 v34, 16, v22
	v_cvt_pk_bf16_f32 v32, v32, v33
	global_store_dword v[30:31], v32, off nt
	v_and_b32_e32 v22, 0xffff0000, v22
	v_mul_f32_e32 v30, v36, v115
	v_mul_f32_e32 v31, v37, v114
	v_mul_f32_e32 v32, v30, v34
	v_mul_f32_e32 v33, v31, v22
	v_rcp_f32_e32 v30, v30
	v_rcp_f32_e32 v31, v31
	v_or_b32_e32 v26, 0x3800, v26
	v_mul_f32_e32 v35, v46, v117
	v_mul_f32_e32 v36, v47, v116
	v_pk_mul_f32 v[28:29], v[28:29], v[30:31]
	v_mul_f32_e32 v22, v36, v22
	v_cvt_pk_bf16_f32 v30, v28, v29
	v_lshl_add_u64 v[28:29], s[36:37], 0, v[26:27]
	global_store_dword v[28:29], v30, off nt
	v_mul_f32_e32 v28, v35, v34
	v_cvt_pk_bf16_f32 v22, v28, v22
	v_rcp_f32_e32 v28, v35
	v_rcp_f32_e32 v29, v36
	v_lshl_add_u64 v[30:31], s[40:41], 0, v[26:27]
	global_store_dword v[30:31], v22, off nt
	v_pk_add_f32 v[30:31], v[46:47], 1.0 op_sel_hi:[1,0] neg_lo:[1,0] neg_hi:[1,0]
	v_cvt_pk_bf16_f32 v37, v32, v33
	v_pk_mul_f32 v[28:29], v[30:31], v[28:29]
	v_lshl_add_u64 v[32:33], s[34:35], 0, v[26:27]
	v_cvt_pk_bf16_f32 v22, v28, v29
	v_lshl_add_u64 v[26:27], s[38:39], 0, v[26:27]
	global_store_dword v[32:33], v37, off nt
	global_store_dword v[26:27], v22, off nt
	s_and_saveexec_b64 s[44:45], s[0:1]
	s_cbranch_execz .LBB0_551
	ds_read_b64 v[26:27], v21 offset:4096
	s_lshl_b32 s42, s42, 3
	v_pk_mul_f32 v[8:9], v[52:53], v[8:9]
	s_or_b32 s42, s42, s50
	v_pk_mul_f32 v[8:9], v[8:9], v[10:11]
	s_waitcnt lgkmcnt(0)
	v_pk_mul_f32 v[0:1], v[26:27], v[0:1]
	s_lshl_b32 s43, s42, 7
	v_pk_mul_f32 v[0:1], v[0:1], v[2:3]
	s_add_i32 s42, s42, 32
	v_pk_mul_f32 v[8:9], v[8:9], v[12:13]
	v_pk_mul_f32 v[0:1], v[0:1], v[4:5]
	s_or_b32 s50, s43, s49
	s_ashr_i32 s43, s42, 31
	v_pk_mul_f32 v[8:9], v[8:9], v[14:15]
	v_pk_mul_f32 v[0:1], v[0:1], v[6:7]
	s_lshl_b64 s[42:43], s[42:43], 7
	s_xor_b32 s49, s49, 0x7f
	v_pk_mul_f32 v[0:1], v[0:1], v[16:17]
	s_or_b32 s42, s42, s49
	v_mad_i64_i32 v[2:3], s[50:51], s50, v96, v[24:25]
	v_pk_mul_f32 v[4:5], v[74:75], v[8:9]
	v_pk_mul_f32 v[0:1], v[0:1], v[18:19]
	global_store_dwordx2 v[2:3], v[52:53], off
	global_store_dwordx2 v[2:3], v[8:9], off offset:512
	global_store_dwordx2 v[2:3], v[4:5], off offset:1024
	s_mul_i32 s49, s43, 0x600
	v_mad_u64_u32 v[2:3], s[42:43], s42, v96, v[24:25]
	v_pk_mul_f32 v[0:1], v[0:1], v[70:71]
	v_add_u32_e32 v3, s49, v3
	global_store_dwordx2 v[2:3], v[68:69], off
	global_store_dwordx2 v[2:3], v[0:1], off offset:512
	v_pk_mul_f32 v[0:1], v[0:1], v[66:67]
	global_store_dwordx2 v[2:3], v[0:1], off offset:1024
	s_branch .LBB0_551
